# qkv finalize (even layers) row loop: loop-top vmcnt(0) no longer drains the previous row's 18 stores (full drain moved to the entry path, vmcnt(18) in the loop)
# speedup vs baseline: 1.0049x; 1.0034x over previous
; __device__ __forceinline__ void qkv_even_phase(const Ctx& F, CParams& P, int e) {
;     ...
;     const int tfirst = F.vcu * 8 + F.wid, tstr = F.G * 8;
;     Raw R; if (tfirst < TT) load_raw(tfirst, R);
;     for (int t = tfirst; t < TT; t += tstr) {
;         const bool latent = t < TL; const int s = t & (SEQ - 1), row = s >> 6, col = s & 63; const int kr = krow_of(t);
;         Raw C = R; { const int tn = t + tstr; load_raw(tn < TT ? tn : t, R); }
.LBB0_1765:
	s_andn2_b64 vcc, exec, s[2:3]
	s_mov_b32 s66, 0x20000
	s_cbranch_vccnz .LBB0_1796
	v_lshl_add_u64 v[52:53], s[0:1], 0, v[32:33]
	s_mov_b64 s[18:19], 0x3ca1c100
	v_mov_b32_e32 v115, v33
	v_lshl_add_u64 v[126:127], v[52:53], 0, s[18:19]
	v_lshl_add_u64 v[52:53], s[0:1], 0, v[114:115]
	s_mov_b64 s[18:19], 0x40c1c100
	v_ashrrev_i32_e32 v107, 31, v106
	v_lshl_add_u64 v[128:129], v[52:53], 0, s[18:19]
	v_lshlrev_b64 v[130:131], 7, v[106:107]
	s_mov_b64 s[18:19], 0x400
	v_cmp_gt_u32_e64 s[2:3], 8, v47
	v_and_b32_e32 v47, 4, v42
	v_lshl_add_u64 v[134:135], v[130:131], 0, s[18:19]
	s_mov_b64 s[18:19], 0x600
	s_movk_i32 s15, 0x180
	s_add_u32 s10, s0, 0x3989c100
	v_cmp_eq_u32_e64 s[4:5], 0, v47
	v_lshl_add_u64 v[136:137], v[130:131], 0, s[18:19]
	v_lshlrev_b64 v[138:139], 3, v[42:43]
	v_mad_i64_i32 v[42:43], s[18:19], v106, s15, 0
	v_mov_b32_e32 v47, 0xc00
	s_addc_u32 s11, s1, 0
	s_lshl_b32 s16, s14, 3
	s_ashr_i32 s7, s6, 31
	v_mad_i64_i32 v[142:143], s[18:19], s6, v47, v[42:43]
	s_ashr_i32 s17, s16, 31
	s_mul_i32 s18, s14, 0x6000
	s_lshl_b64 s[14:15], s[6:7], 11
	s_add_u32 s14, s14, 0x3eb1c500
	v_add_u32_e32 v122, 4, v106
	s_addc_u32 s15, s15, 0
	v_lshlrev_b32_e32 v124, 8, v122
	v_ashrrev_i32_e32 v49, 31, v48
	v_ashrrev_i32_e32 v123, 31, v122
	v_mov_b32_e32 v47, v33
	v_lshl_add_u64 v[146:147], s[14:15], 0, v[130:131]
	v_ashrrev_i32_e32 v117, 31, v116
	v_ashrrev_i32_e32 v125, 31, v124
	v_ashrrev_i32_e32 v119, 31, v118
	v_ashrrev_i32_e32 v121, 31, v120
	v_lshlrev_b64 v[132:133], 7, v[122:123]
	v_lshl_add_u64 v[144:145], v[142:143], 0, v[46:47]
	s_mul_hi_i32 s19, s16, 0xc00
	v_or_b32_e32 v146, v146, v50
	s_lshl_b64 s[20:21], s[16:17], 11
	v_or_b32_e32 v142, v142, v50
	v_lshlrev_b32_e32 v206, 2, v51
	v_lshlrev_b64 v[148:149], 1, v[44:45]
	v_lshlrev_b64 v[150:151], 1, v[48:49]
	s_waitcnt vmcnt(0)
	s_branch .LBB0_1768

; #define UNP4(W, X) do { X[0] = bf_lo(W.x); X[1] = bf_hi(W.x); X[2] = bf_lo(W.y); X[3] = bf_hi(W.y); } while (0)
; __device__ __forceinline__ void qkv_even_phase(const Ctx& F, CParams& P, int e) {
;     ...
;     auto load_raw = [&](int t, Raw& R) {
;         const bf16_t* p1 = P1 + (size_t)t * AB_INP;
;         { const int s_ = t & (SEQ - 1), pos_ = (q16 >> 3) ? (s_ & 63) : (s_ >> 6); const float* tp = t16 + (pos_ * 16 + (q16 & 3) * 4) * 2; R.rc0 = *(const f32x4*)tp; R.rc1 = *(const f32x4*)(tp + 4); }
; #pragma unroll
;         for (int j = 0; j < 3; ++j) R.cq[j] = *(const u32x2*)(p1 + j * 256 + F.lane * 4);
;         R.ckv = *(const u32x4*)(p1 + 768 + F.lane * 8);
;         R.kro = *(const u32x2*)(p1 + 1280 + q16 * 4);
; #pragma unroll
;         for (int ps = 0; ps < 2; ++ps) { const int h = ps * 4 + grp; const bf16_t* src = QA + (size_t)t * 1536 + h * 192;
;             R.qn[ps] = *(const u32x4*)(src + q16 * 8); R.qr[ps] = *(const u32x2*)(src + 128 + q16 * 4);
;             const bf16_t* sk = KV + (size_t)t * 2048 + h * 256; R.kn[ps] = *(const u32x4*)(sk + q16 * 8); R.kv[ps] = *(const u32x4*)(sk + 128 + q16 * 8); }
; #pragma unroll
;         for (int ps = 0; ps < 4; ++ps) { const int hm = ps * 4 + grp; R.dq[ps] = *(const u32x2*)(p1 + 1344 + hm * 64 + q16 * 4); R.dk[ps] = *(const u32x2*)(p1 + 2368 + hm * 64 + q16 * 4); }
;     };
;     ...
;     const int tfirst = F.vcu * 8 + F.wid, tstr = F.G * 8;
;     Raw R; if (tfirst < TT) load_raw(tfirst, R);
;     for (int t = tfirst; t < TT; t += tstr) {
;         const bool latent = t < TL; const int s = t & (SEQ - 1), row = s >> 6, col = s & 63; const int kr = krow_of(t);
;         Raw C = R; { const int tn = t + tstr; load_raw(tn < TT ? tn : t, R); }
;         const float rcs[4] = {C.rc0[0], C.rc0[2], C.rc1[0], C.rc1[2]}, rsn[4] = {C.rc0[1], C.rc0[3], C.rc1[1], C.rc1[3]}; const bool rfirst = (q16 & 7) < 4;
;     ...
;         float ss = 0.f;
; #pragma unroll
;         for (int j = 0; j < 3; ++j) { float x[4]; UNP4(C.cq[j], x); ss += x[0] * x[0] + x[1] * x[1] + x[2] * x[2] + x[3] * x[3]; }
;         ss = wave_sum(ss); const float rstd_q = rsqrtf(ss * (1.f / 768.f) + EPS);
;         float s2 = 0.f;
;         { float x[8]; UNP8(C.ckv, x);
; #pragma unroll
;           for (int i = 0; i < 8; ++i) s2 += x[i] * x[i]; }
;         s2 = wave_sum(s2); const float rstd_kv = rsqrtf(s2 * (1.f / 512.f) + EPS);
.LBB0_1772:
	s_waitcnt vmcnt(18)
	v_and_b32_e32 v77, 0xffff0000, v204
	v_lshlrev_b32_e32 v76, 16, v204
	v_mul_f32_e32 v77, v77, v77
	v_lshlrev_b32_e32 v164, 16, v205
	v_fmac_f32_e32 v77, v76, v76
	v_fmac_f32_e32 v77, v164, v164
	v_and_b32_e32 v164, 0xffff0000, v202
	v_and_b32_e32 v165, 0xffff0000, v205
	v_lshlrev_b32_e32 v76, 16, v202
	v_mul_f32_e32 v164, v164, v164
	v_fmac_f32_e32 v77, v165, v165
	v_lshlrev_b32_e32 v165, 16, v203
	v_fmac_f32_e32 v164, v76, v76
	v_and_b32_e32 v168, 0xffff0000, v203
	v_fmac_f32_e32 v164, v165, v165
	v_fmac_f32_e32 v164, v168, v168
	v_add_f32_e32 v76, v77, v164
	v_and_b32_e32 v164, 0xffff0000, v200
	v_lshlrev_b32_e32 v77, 16, v200
	v_mul_f32_e32 v164, v164, v164
	s_add_i32 s17, s6, s16
	v_lshlrev_b32_e32 v165, 16, v201
	v_fmac_f32_e32 v164, v77, v77
	s_cmpk_gt_i32 s17, 0x41ff
	v_and_b32_e32 v168, 0xffff0000, v201
	v_fmac_f32_e32 v164, v165, v165
	s_cselect_b64 s[22:23], -1, 0
	s_cmpk_lt_i32 s17, 0x4200
	v_fmac_f32_e32 v164, v168, v168
	s_cselect_b32 s34, s17, s6
	v_add_f32_e32 v168, v76, v164
	s_ashr_i32 s35, s34, 31
	s_mul_i32 s6, s34, 0x2400
	ds_swizzle_b32 v169, v168 offset:swizzle(SWAP,16)
	s_mul_hi_i32 s7, s34, 0x2400
	s_add_u32 s6, s31, s6
	s_addc_u32 s7, s33, s7
	s_and_b32 s25, s34, 63
	s_bfe_u32 s37, s34, 0x70006
	v_mov_b32_e32 v42, s25
	v_mov_b32_e32 v43, s37
	s_mul_hi_i32 s25, s34, 0xc00
	s_mul_i32 s37, s34, 0xc00
	s_lshl_b64 s[34:35], s[34:35], 12
	s_add_u32 s38, s27, s37
	s_addc_u32 s39, s28, s25
	s_waitcnt lgkmcnt(0)
	v_add_f32_e32 v172, v168, v169
	s_add_u32 s34, s29, s34
	ds_swizzle_b32 v173, v172 offset:swizzle(SWAP,8)
	s_addc_u32 s35, s30, s35
	v_lshl_add_u64 v[60:61], v[112:113], 1, s[34:35]
	v_lshl_add_u64 v[72:73], v[124:125], 1, s[34:35]
	s_add_u32 s34, s6, 0x1280
	s_addc_u32 s35, s7, 0
	v_lshlrev_b32_e32 v183, 16, v102
	v_and_b32_e32 v102, 0xffff0000, v102
	v_mov_b32_e32 v115, v33
	v_lshl_add_u64 v[58:59], v[110:111], 1, s[38:39]
	v_lshl_add_u64 v[70:71], v[116:117], 1, s[38:39]
	v_lshl_add_u64 v[76:77], s[6:7], 0, v[148:149]
	v_lshl_add_u64 v[168:169], s[34:35], 0, v[148:149]
	v_mul_f32_e32 v203, v102, v102
	v_lshl_add_u64 v[176:177], s[6:7], 0, v[114:115]
	v_lshl_add_u64 v[52:53], v[58:59], 0, v[32:33]
	v_lshl_add_u64 v[58:59], v[58:59], 0, v[114:115]
	v_lshl_add_u64 v[66:67], v[70:71], 0, v[32:33]
	v_lshl_add_u64 v[70:71], v[70:71], 0, v[114:115]
	v_lshl_add_u64 v[174:175], v[76:77], 0, v[114:115]
	v_lshl_add_u64 v[168:169], v[168:169], 0, v[114:115]
	v_lshl_add_u64 v[178:179], s[34:35], 0, v[114:115]
	s_waitcnt lgkmcnt(0)
	v_add_f32_e32 v115, v172, v173
	v_lshlrev_b32_e32 v200, 16, v103
	v_fmac_f32_e32 v203, v183, v183
	ds_swizzle_b32 v182, v115 offset:swizzle(SWAP,4)
	v_and_b32_e32 v103, 0xffff0000, v103
	v_fmac_f32_e32 v203, v200, v200
	v_lshlrev_b32_e32 v201, 16, v104
	v_fmac_f32_e32 v203, v103, v103
	v_and_b32_e32 v104, 0xffff0000, v104
	v_fmac_f32_e32 v203, v201, v201
	v_lshlrev_b32_e32 v202, 16, v105
	v_fmac_f32_e32 v203, v104, v104
	v_and_b32_e32 v105, 0xffff0000, v105
	v_fmac_f32_e32 v203, v202, v202
	s_waitcnt lgkmcnt(0)
	v_add_f32_e32 v115, v115, v182
	v_fmac_f32_e32 v203, v105, v105
	ds_swizzle_b32 v182, v115 offset:swizzle(SWAP,2)
	ds_swizzle_b32 v183, v203 offset:swizzle(SWAP,16)
	v_cndmask_b32_e64 v42, v42, v43, s[2:3]
	v_lshl_or_b32 v42, v42, 7, v206
	v_lshl_add_u64 v[50:51], v[108:109], 1, s[6:7]
	global_load_dwordx4 v[46:49], v42, s[8:9] offset:16
	s_nop 0
	global_load_dwordx4 v[42:45], v42, s[8:9]
	s_nop 0
	global_load_dwordx2 v[154:155], v[50:51], off
	global_load_dwordx2 v[156:157], v[50:51], off offset:512
	global_load_dwordx2 v[158:159], v[50:51], off offset:1024
	v_lshl_add_u64 v[50:51], v[50:51], 0, v[138:139]
	v_lshl_add_u64 v[62:63], v[60:61], 0, v[32:33]
	v_lshl_add_u64 v[74:75], v[72:73], 0, v[32:33]
	v_lshl_add_u64 v[170:171], v[118:119], 1, v[178:179]
	v_lshl_add_u64 v[180:181], v[120:121], 1, v[178:179]
	global_load_dwordx4 v[54:57], v[50:51], off offset:1536
	s_nop 0
	global_load_dwordx4 v[50:53], v[52:53], off
	s_nop 0
	global_load_dwordx2 v[160:161], v[58:59], off offset:256
	s_nop 0
	global_load_dwordx4 v[58:61], v[62:63], off
	s_nop 0
	global_load_dwordx4 v[62:65], v[62:63], off offset:256
	s_nop 0
	global_load_dwordx4 v[66:69], v[66:67], off
	s_nop 0
	global_load_dwordx2 v[162:163], v[70:71], off offset:256
	s_nop 0
	global_load_dwordx4 v[70:73], v[74:75], off
	s_nop 0
	global_load_dwordx4 v[74:77], v[74:75], off offset:256
	s_nop 0
	global_load_dwordx2 v[164:165], v[174:175], off offset:2688
	s_nop 0
	global_load_dwordx2 v[168:169], v[168:169], off
	s_nop 0
	global_load_dwordx2 v[172:173], v[174:175], off offset:3200
	s_nop 0
	global_load_dwordx2 v[170:171], v[170:171], off
	s_nop 0
	global_load_dwordx2 v[174:175], v[174:175], off offset:3712
	v_lshl_add_u64 v[102:103], v[176:177], 0, v[150:151]
	v_lshl_add_u64 v[104:105], v[178:179], 0, v[150:151]
	s_waitcnt lgkmcnt(1)
; __device__ __forceinline__ float grp16_sum(float v) { DPP_ADD(v, 0xB1); DPP_ADD(v, 0x4E); DPP_ADD(v, 0x141); DPP_ADD(v, 0x140); return v; }
; #define UNP8(W, X) do { X[0] = bf_lo(W.x); X[1] = bf_hi(W.x); X[2] = bf_lo(W.y); X[3] = bf_hi(W.y); X[4] = bf_lo(W.z); X[5] = bf_hi(W.z); X[6] = bf_lo(W.w); X[7] = bf_hi(W.w); } while (0)
; #define UNP4(W, X) do { X[0] = bf_lo(W.x); X[1] = bf_hi(W.x); X[2] = bf_lo(W.y); X[3] = bf_hi(W.y); } while (0)
; #define ROPE4V(X) do { _Pragma("unroll") for (int e_ = 0; e_ < 4; ++e_) { const float p_ = swz_xor<4>(X[e_]); X[e_] = rfirst ? X[e_] * rcs[e_] - p_ * rsn[e_] : p_ * rsn[e_] + X[e_] * rcs[e_]; } } while (0)
; __device__ __forceinline__ void qkv_even_phase(const Ctx& F, CParams& P, int e) {
;     ...
;         for (int j = 0; j < 3; ++j) { float x[4]; UNP4(C.cq[j], x); ss += x[0] * x[0] + x[1] * x[1] + x[2] * x[2] + x[3] * x[3]; }
;         ss = wave_sum(ss); const float rstd_q = rsqrtf(ss * (1.f / 768.f) + EPS);
;         float s2 = 0.f;
;         { float x[8]; UNP8(C.ckv, x);
; #pragma unroll
;           for (int i = 0; i < 8; ++i) s2 += x[i] * x[i]; }
;         s2 = wave_sum(s2); const float rstd_kv = rsqrtf(s2 * (1.f / 512.f) + EPS);
;         float kro[4]; UNP4(C.kro, kro);
; #pragma unroll
;         for (int ps = 0; ps < 2; ++ps) { const int h = ps * 4 + grp;
;             float xn[8], xr[4]; UNP8(C.qn[ps], xn); UNP4(C.qr[ps], xr);
;             float sq = 0.f;
; #pragma unroll
;             for (int i = 0; i < 8; ++i) { xn[i] *= rstd_q; sq += xn[i] * xn[i]; }
; #pragma unroll
;             for (int i = 0; i < 4; ++i) { xr[i] *= rstd_q; sq += xr[i] * xr[i]; }
;             sq = grp16_sum(sq); const float r = rsqrtf(sq * (1.f / 192.f) + EPS);
;             const float rq = r * (0.07216878364870322f * LOG2E);
; #pragma unroll
;             for (int i = 0; i < 8; ++i) xn[i] *= rq * gq_n[i];
; #pragma unroll
;             for (int i = 0; i < 4; ++i) xr[i] *= rq * gq_r[i];
;             if (latent) ROPE4V(xr);
	v_add_f32_e32 v115, v115, v182
	s_waitcnt lgkmcnt(0)
	v_add_f32_e32 v201, v203, v183
	global_load_dwordx2 v[182:183], v114, s[6:7] offset:2560
	global_load_dwordx2 v[176:177], v[180:181], off
	s_nop 0
	global_load_dwordx2 v[180:181], v[102:103], off offset:2688
	global_load_dwordx2 v[178:179], v[104:105], off
	ds_swizzle_b32 v202, v201 offset:swizzle(SWAP,8)
	ds_swizzle_b32 v200, v115 offset:swizzle(SWAP,1)
	s_waitcnt lgkmcnt(1)
	v_add_f32_e32 v104, v201, v202
	ds_swizzle_b32 v105, v104 offset:swizzle(SWAP,4)
	s_waitcnt lgkmcnt(1)
	v_add_f32_e32 v102, v115, v200
	v_mov_b32_e32 v103, v102
	s_nop 1
	v_permlane32_swap_b32_e32 v102, v103
	v_add_f32_e32 v102, v102, v103
	s_waitcnt lgkmcnt(0)
	v_add_f32_e32 v103, v104, v105
	ds_swizzle_b32 v104, v103 offset:swizzle(SWAP,2)
	v_fmamk_f32 v102, v102, 0x3aaaaaab, v234
	v_mul_f32_e32 v105, 0x4b800000, v102
	v_cmp_gt_f32_e32 vcc, s57, v102
	v_lshlrev_b32_e32 v200, 16, v100
	s_waitcnt lgkmcnt(0)
	v_add_f32_e32 v103, v103, v104
	v_cndmask_b32_e32 v102, v102, v105, vcc
	v_rsq_f32_e32 v102, v102
	ds_swizzle_b32 v104, v103 offset:swizzle(SWAP,1)
	v_and_b32_e32 v100, 0xffff0000, v100
	v_mul_f32_e32 v105, 0x45800000, v102
	v_cndmask_b32_e32 v102, v102, v105, vcc
	s_waitcnt lgkmcnt(0)
	v_add_f32_e32 v115, v103, v104
	v_lshlrev_b32_e32 v103, 16, v98
	v_and_b32_e32 v98, 0xffff0000, v98
	v_mul_f32_e32 v105, v102, v98
	v_lshlrev_b32_e32 v104, 16, v99
	v_mul_f32_e32 v201, v102, v103
	v_mul_f32_e32 v103, v105, v105
	v_and_b32_e32 v99, 0xffff0000, v99
	v_fmac_f32_e32 v103, v201, v201
	v_mul_f32_e32 v202, v102, v104
	v_fmac_f32_e32 v103, v202, v202
	v_mul_f32_e32 v203, v102, v99
	v_fmac_f32_e32 v103, v203, v203
	v_mul_f32_e32 v204, v102, v200
	v_fmac_f32_e32 v103, v204, v204
	v_mul_f32_e32 v205, v102, v100
	v_fmac_f32_e32 v103, v205, v205
	v_and_b32_e32 v98, 0xffff0000, v101
	v_lshlrev_b32_e32 v99, 16, v101
	v_pk_mul_f32 v[98:99], v[102:103], v[98:99] op_sel_hi:[0,1]
	v_pk_mul_f32 v[100:101], v[98:99], v[98:99]
	v_mov_b32_e32 v200, v115
	v_add_f32_e32 v101, v101, v103
	v_add_f32_e32 v103, v100, v101
	v_and_b32_e32 v101, 0xffff0000, v199
	v_lshlrev_b32_e32 v100, 16, v199
	v_and_b32_e32 v199, 0xffff0000, v198
	v_lshlrev_b32_e32 v198, 16, v198
	v_pk_mul_f32 v[198:199], v[102:103], v[198:199] op_sel_hi:[0,1]
	v_pk_mul_f32 v[216:217], v[198:199], v[198:199]
	v_pk_mul_f32 v[208:209], v[102:103], v[100:101] op_sel_hi:[0,1]
	v_add_f32_e32 v103, v216, v103
	v_pk_mul_f32 v[100:101], v[208:209], v[208:209]
	v_add_f32_e32 v103, v217, v103
	v_add_f32_e32 v100, v100, v103
	v_add_f32_e32 v100, v101, v100
	v_cndmask_b32_e64 v103, 0, 1, s[14:15]
	v_permlane32_swap_b32_e32 v115, v200
	v_add_f32_dpp v100, v100, v100 quad_perm:[1,0,3,2] row_mask:0xf bank_mask:0xf bound_ctrl:1
	v_cmp_ne_u32_e64 s[6:7], 1, v103
	s_nop 0
	v_add_f32_dpp v100, v100, v100 quad_perm:[2,3,0,1] row_mask:0xf bank_mask:0xf bound_ctrl:1
	s_nop 1
	v_add_f32_dpp v100, v100, v100 row_half_mirror row_mask:0xf bank_mask:0xf bound_ctrl:1
	s_nop 1
	v_add_f32_dpp v100, v100, v100 row_mirror row_mask:0xf bank_mask:0xf bound_ctrl:1
	v_fmamk_f32 v100, v100, 0x3baaaaab, v234
	v_mul_f32_e32 v101, 0x4b800000, v100
	v_cmp_gt_f32_e32 vcc, s57, v100
	s_nop 1
	v_cndmask_b32_e32 v100, v100, v101, vcc
	v_rsq_f32_e32 v100, v100
	s_nop 0
	v_mul_f32_e32 v101, 0x45800000, v100
	v_cndmask_b32_e32 v100, v100, v101, vcc
	v_mul_f32_e32 v104, 0x3dd53b94, v100
	v_pk_mul_f32 v[100:101], v[16:17], v[104:105] op_sel_hi:[1,0]
	s_andn2_b64 vcc, exec, s[14:15]
	v_pk_mul_f32 v[100:101], v[198:199], v[100:101]
	v_pk_mul_f32 v[198:199], v[18:19], v[104:105] op_sel_hi:[1,0]
	s_nop 0
	v_pk_mul_f32 v[198:199], v[208:209], v[198:199]
	s_cbranch_vccnz .LBB0_1774
	ds_swizzle_b32 v208, v100 offset:swizzle(SWAP,4)
	ds_swizzle_b32 v209, v101 offset:swizzle(SWAP,4)
	v_mov_b32_e32 v218, v39
	v_mov_b32_e32 v219, v41
	v_mov_b32_e32 v216, v38
	v_mov_b32_e32 v217, v40
	s_waitcnt lgkmcnt(0)
	v_pk_mul_f32 v[208:209], v[218:219], v[208:209]
	v_mov_b32_e32 v218, v35
	v_cndmask_b32_e64 v209, v209, -v209, s[4:5]
	v_cndmask_b32_e64 v208, v208, -v208, s[4:5]
	v_pk_fma_f32 v[100:101], v[216:217], v[100:101], v[208:209]
	ds_swizzle_b32 v208, v198 offset:swizzle(SWAP,4)
	ds_swizzle_b32 v209, v199 offset:swizzle(SWAP,4)
	v_mov_b32_e32 v219, v37
	v_mov_b32_e32 v216, v34
	v_mov_b32_e32 v217, v36
	s_waitcnt lgkmcnt(0)
	v_pk_mul_f32 v[208:209], v[218:219], v[208:209]
	s_nop 0
	v_cndmask_b32_e64 v209, v209, -v209, s[4:5]
	v_cndmask_b32_e64 v208, v208, -v208, s[4:5]
	v_pk_fma_f32 v[198:199], v[216:217], v[198:199], v[208:209]
